# v38 + G4 gate epilogue: in-place U loads and the four bias values prefetched up to three rows ahead (was 16 serial load-wait-store round trips per tile)
# speedup vs baseline: 1.0053x; 1.0053x over previous
; __device__ __forceinline__ unsigned cvt_pk_bf16(float lo, float hi) { unsigned r; asm volatile("v_cvt_pk_bf16_f32 %0, %1, %2" : "=v"(r) : "v"(lo), "v"(hi)); return r; }
; __device__ __forceinline__ float bf_lo(unsigned w) { return __uint_as_float(w << 16); }
; __device__ __forceinline__ float bf_hi(unsigned w) { return __uint_as_float(w & 0xffff0000u); }
;     __device__ __forceinline__ void operator()(const f32x4 (&acc)[2][2][4][2], const Unit& u, int wr, int wc, int fr, int fq) const {
;     ...
;         for (int ai = 0; ai < 2; ++ai)
; #pragma unroll
;             for (int m = 0; m < 4; ++m) { const int row = row0 + ai * HALF + m * 16; const float bias = bs[u.pn * 128 + (row & 127)];
;                 bf16_t* rowp = U + (size_t)row * ldc + col0;
; #pragma unroll
;                 for (int bj = 0; bj < 2; ++bj) { const u32x4 uu = *(const u32x4*)(rowp + bj * HALF);
;                     const f32x4 a0 = acc[ai][bj][m][0] + bias, a1 = acc[ai][bj][m][1] + bias;
;                     u32x4 w; w.x = cvt_pk_bf16(bf_lo(uu.x) * a0[0], bf_hi(uu.x) * a0[1]); w.y = cvt_pk_bf16(bf_lo(uu.y) * a0[2], bf_hi(uu.y) * a0[3]);
;                     w.z = cvt_pk_bf16(bf_lo(uu.z) * a1[0], bf_hi(uu.z) * a1[1]); w.w = cvt_pk_bf16(bf_lo(uu.w) * a1[2], bf_hi(uu.w) * a1[3]);
;                     *(u32x4*)(rowp + bj * HALF) = w; } }
.LBB0_439:
	s_lshl_b32 s8, s30, 7
	v_lshl_add_u32 v136, s34, 8, v142
	v_or_b32_e32 v138, s8, v144
	v_lshl_or_b32 v134, s30, 8, v145
	v_ashrrev_i32_e32 v139, 31, v138
	v_ashrrev_i32_e32 v137, 31, v136
	v_ashrrev_i32_e32 v135, 31, v134
	v_lshl_add_u64 v[140:141], v[138:139], 2, s[18:19]
	v_lshlrev_b64 v[138:139], 12, v[136:137]
	v_lshl_add_u64 v[138:139], s[16:17], 0, v[138:139]
	v_lshlrev_b64 v[134:135], 1, v[134:135]
	v_lshl_add_u64 v[138:139], v[138:139], 0, v[134:135]
	v_lshl_add_u32 v192, v136, 12, v134
	global_load_dword v184, v[140:141], off
	global_load_dword v185, v[140:141], off offset:64
	global_load_dword v186, v[140:141], off offset:128
	global_load_dword v187, v[140:141], off offset:192
	v_mov_b32_e32 v193, v192
	global_load_dwordx4 v[156:159], v193, s[16:17]
	global_load_dwordx4 v[160:163], v193, s[16:17] offset:256
	v_add_u32_e32 v193, 0x10000, v192
	global_load_dwordx4 v[164:167], v193, s[16:17]
	global_load_dwordx4 v[168:171], v193, s[16:17] offset:256
	v_add_u32_e32 v193, 0x20000, v192
	global_load_dwordx4 v[176:179], v193, s[16:17]
	global_load_dwordx4 v[180:183], v193, s[16:17] offset:256
	s_waitcnt vmcnt(9)
	s_nop 2
	v_mov_b32_e32 v152, v184
	s_waitcnt vmcnt(5)
	s_nop 2
	v_mov_b32_e32 v148, v156
	v_mov_b32_e32 v149, v157
	v_mov_b32_e32 v150, v158
	v_mov_b32_e32 v151, v159
	s_movk_i32 s9, 0x5f
	s_mov_b64 s[36:37], 0x80000
	v_readlane_b32 s76, v255, 3
	v_readlane_b32 s77, v255, 4
	v_readlane_b32 s78, v255, 5
	s_mov_b32 s70, 0xbf3a00e3
	v_readlane_b32 s79, v255, 6
	v_pk_add_f32 v[124:125], v[124:125], v[152:153] op_sel_hi:[1,0]
	v_pk_add_f32 v[154:155], v[122:123], v[152:153] op_sel_hi:[1,0]
	v_pk_add_f32 v[122:123], v[120:121], v[152:153] op_sel_hi:[1,0]
	v_lshlrev_b32_e32 v120, 16, v148
	v_and_b32_e32 v121, 0xffff0000, v148
	v_mul_f32_e32 v120, v124, v120
	v_mul_f32_e32 v121, v125, v121
	v_pk_add_f32 v[126:127], v[126:127], v[152:153] op_sel_hi:[1,0]
	v_cvt_pk_bf16_f32 v120, v120, v121
	v_lshlrev_b32_e32 v121, 16, v149
	v_and_b32_e32 v124, 0xffff0000, v149
	v_mul_f32_e32 v121, v126, v121
	v_mul_f32_e32 v124, v127, v124
	v_cvt_pk_bf16_f32 v121, v121, v124
	v_lshlrev_b32_e32 v124, 16, v150
	v_mul_f32_e32 v122, v122, v124
	v_and_b32_e32 v124, 0xffff0000, v150
	v_mul_f32_e32 v123, v123, v124
	v_cvt_pk_bf16_f32 v122, v122, v123
	v_lshlrev_b32_e32 v123, 16, v151
	v_mul_f32_e32 v123, v154, v123
	v_and_b32_e32 v124, 0xffff0000, v151
	v_mul_f32_e32 v124, v155, v124
	v_cvt_pk_bf16_f32 v123, v123, v124
	global_store_dwordx4 v[138:139], v[120:123], off
	s_waitcnt vmcnt(5)
	s_nop 2
	v_mov_b32_e32 v120, v160
	v_mov_b32_e32 v121, v161
	v_mov_b32_e32 v122, v162
	v_mov_b32_e32 v123, v163
	v_add_u32_e32 v193, 0x30000, v192
	global_load_dwordx4 v[156:159], v193, s[16:17]
	global_load_dwordx4 v[160:163], v193, s[16:17] offset:256
	v_pk_add_f32 v[116:117], v[116:117], v[152:153] op_sel_hi:[1,0]
	v_pk_add_f32 v[124:125], v[114:115], v[152:153] op_sel_hi:[1,0]
	v_pk_add_f32 v[114:115], v[112:113], v[152:153] op_sel_hi:[1,0]
	v_pk_add_f32 v[118:119], v[118:119], v[152:153] op_sel_hi:[1,0]
	v_lshlrev_b32_e32 v112, 16, v120
	v_and_b32_e32 v113, 0xffff0000, v120
	v_mul_f32_e32 v112, v116, v112
	v_mul_f32_e32 v113, v117, v113
	v_cvt_pk_bf16_f32 v112, v112, v113
	v_lshlrev_b32_e32 v113, 16, v121
	v_and_b32_e32 v116, 0xffff0000, v121
	v_mul_f32_e32 v113, v118, v113
	v_mul_f32_e32 v116, v119, v116
	v_cvt_pk_bf16_f32 v113, v113, v116
	v_lshlrev_b32_e32 v116, 16, v122
	v_mul_f32_e32 v114, v114, v116
	v_and_b32_e32 v116, 0xffff0000, v122
	v_mul_f32_e32 v115, v115, v116
	v_cvt_pk_bf16_f32 v114, v114, v115
	v_lshlrev_b32_e32 v115, 16, v123
	v_mul_f32_e32 v115, v124, v115
	v_and_b32_e32 v116, 0xffff0000, v123
	v_mul_f32_e32 v116, v125, v116
	v_cvt_pk_bf16_f32 v115, v115, v116
	global_store_dwordx4 v[138:139], v[112:115], off offset:256
	s_nop 1
	v_or_b32_e32 v114, 16, v136
	v_bitop3_b32 v112, v136, s9, 16 bitop3:0xc8
	v_ashrrev_i32_e32 v115, 31, v114
	v_or_b32_e32 v112, s8, v112
	v_lshlrev_b64 v[114:115], 12, v[114:115]
	v_ashrrev_i32_e32 v113, 31, v112
	v_lshl_add_u64 v[114:115], s[16:17], 0, v[114:115]
	v_lshl_add_u64 v[112:113], v[112:113], 2, s[18:19]
	v_lshl_add_u64 v[114:115], v[114:115], 0, v[134:135]
	s_waitcnt vmcnt(12)
	s_nop 2
	v_mov_b32_e32 v112, v185
	s_movk_i32 s9, 0x6f
	s_waitcnt vmcnt(7)
	s_nop 2
	v_mov_b32_e32 v116, v164
	v_mov_b32_e32 v117, v165
	v_mov_b32_e32 v118, v166
	v_mov_b32_e32 v119, v167
	v_pk_add_f32 v[108:109], v[108:109], v[112:113] op_sel_hi:[1,0]
	v_pk_add_f32 v[120:121], v[106:107], v[112:113] op_sel_hi:[1,0]
	v_pk_add_f32 v[106:107], v[104:105], v[112:113] op_sel_hi:[1,0]
	v_lshlrev_b32_e32 v104, 16, v116
	v_and_b32_e32 v105, 0xffff0000, v116
	v_mul_f32_e32 v104, v108, v104
	v_mul_f32_e32 v105, v109, v105
	v_pk_add_f32 v[110:111], v[110:111], v[112:113] op_sel_hi:[1,0]
	v_cvt_pk_bf16_f32 v104, v104, v105
	v_lshlrev_b32_e32 v105, 16, v117
	v_and_b32_e32 v108, 0xffff0000, v117
	v_mul_f32_e32 v105, v110, v105
	v_mul_f32_e32 v108, v111, v108
	v_cvt_pk_bf16_f32 v105, v105, v108
	v_lshlrev_b32_e32 v108, 16, v118
	v_mul_f32_e32 v106, v106, v108
	v_and_b32_e32 v108, 0xffff0000, v118
	v_mul_f32_e32 v107, v107, v108
	v_cvt_pk_bf16_f32 v106, v106, v107
	v_lshlrev_b32_e32 v107, 16, v119
	v_mul_f32_e32 v107, v120, v107
	v_and_b32_e32 v108, 0xffff0000, v119
	v_mul_f32_e32 v108, v121, v108
	v_cvt_pk_bf16_f32 v107, v107, v108
	global_store_dwordx4 v[114:115], v[104:107], off
	s_waitcnt vmcnt(7)
; __device__ __forceinline__ unsigned cvt_pk_bf16(float lo, float hi) { unsigned r; asm volatile("v_cvt_pk_bf16_f32 %0, %1, %2" : "=v"(r) : "v"(lo), "v"(hi)); return r; }
; __device__ __forceinline__ float bf_lo(unsigned w) { return __uint_as_float(w << 16); }
; __device__ __forceinline__ float bf_hi(unsigned w) { return __uint_as_float(w & 0xffff0000u); }
;     __device__ __forceinline__ void operator()(const f32x4 (&acc)[2][2][4][2], const Unit& u, int wr, int wc, int fr, int fq) const {
;     ...
;         for (int ai = 0; ai < 2; ++ai)
; #pragma unroll
;             for (int m = 0; m < 4; ++m) { const int row = row0 + ai * HALF + m * 16; const float bias = bs[u.pn * 128 + (row & 127)];
;                 bf16_t* rowp = U + (size_t)row * ldc + col0;
; #pragma unroll
;                 for (int bj = 0; bj < 2; ++bj) { const u32x4 uu = *(const u32x4*)(rowp + bj * HALF);
;                     const f32x4 a0 = acc[ai][bj][m][0] + bias, a1 = acc[ai][bj][m][1] + bias;
;                     u32x4 w; w.x = cvt_pk_bf16(bf_lo(uu.x) * a0[0], bf_hi(uu.x) * a0[1]); w.y = cvt_pk_bf16(bf_lo(uu.y) * a0[2], bf_hi(uu.y) * a0[3]);
;                     w.z = cvt_pk_bf16(bf_lo(uu.z) * a1[0], bf_hi(uu.z) * a1[1]); w.w = cvt_pk_bf16(bf_lo(uu.w) * a1[2], bf_hi(uu.w) * a1[3]);
;                     *(u32x4*)(rowp + bj * HALF) = w; } }
	s_nop 2
	v_mov_b32_e32 v104, v168
	v_mov_b32_e32 v105, v169
	v_mov_b32_e32 v106, v170
	v_mov_b32_e32 v107, v171
	v_add_u32_e32 v193, 0x80000, v192
	global_load_dwordx4 v[164:167], v193, s[16:17]
	global_load_dwordx4 v[168:171], v193, s[16:17] offset:256
	v_pk_add_f32 v[100:101], v[100:101], v[112:113] op_sel_hi:[1,0]
	v_pk_add_f32 v[108:109], v[98:99], v[112:113] op_sel_hi:[1,0]
	v_pk_add_f32 v[98:99], v[96:97], v[112:113] op_sel_hi:[1,0]
	v_pk_add_f32 v[102:103], v[102:103], v[112:113] op_sel_hi:[1,0]
	v_lshlrev_b32_e32 v96, 16, v104
	v_and_b32_e32 v97, 0xffff0000, v104
	v_mul_f32_e32 v96, v100, v96
	v_mul_f32_e32 v97, v101, v97
	v_cvt_pk_bf16_f32 v96, v96, v97
	v_lshlrev_b32_e32 v97, 16, v105
	v_and_b32_e32 v100, 0xffff0000, v105
	v_mul_f32_e32 v97, v102, v97
	v_mul_f32_e32 v100, v103, v100
	v_cvt_pk_bf16_f32 v97, v97, v100
	v_lshlrev_b32_e32 v100, 16, v106
	v_mul_f32_e32 v98, v98, v100
	v_and_b32_e32 v100, 0xffff0000, v106
	v_mul_f32_e32 v99, v99, v100
	v_cvt_pk_bf16_f32 v98, v98, v99
	v_lshlrev_b32_e32 v99, 16, v107
	v_mul_f32_e32 v99, v108, v99
	v_and_b32_e32 v100, 0xffff0000, v107
	v_mul_f32_e32 v100, v109, v100
	v_cvt_pk_bf16_f32 v99, v99, v100
	global_store_dwordx4 v[114:115], v[96:99], off offset:256
	s_nop 1
	v_or_b32_e32 v98, 32, v136
	v_bitop3_b32 v96, v136, s9, 32 bitop3:0xc8
	v_ashrrev_i32_e32 v99, 31, v98
	v_or_b32_e32 v96, s8, v96
	v_lshlrev_b64 v[98:99], 12, v[98:99]
	v_ashrrev_i32_e32 v97, 31, v96
	v_lshl_add_u64 v[98:99], s[16:17], 0, v[98:99]
	v_lshl_add_u64 v[96:97], v[96:97], 2, s[18:19]
	v_lshl_add_u64 v[98:99], v[98:99], 0, v[134:135]
	s_waitcnt vmcnt(15)
	s_nop 2
	v_mov_b32_e32 v96, v186
	s_movk_i32 s9, 0x7f
	s_waitcnt vmcnt(9)
	s_nop 2
	v_mov_b32_e32 v100, v176
	v_mov_b32_e32 v101, v177
	v_mov_b32_e32 v102, v178
	v_mov_b32_e32 v103, v179
	v_pk_add_f32 v[92:93], v[92:93], v[96:97] op_sel_hi:[1,0]
	v_pk_add_f32 v[104:105], v[90:91], v[96:97] op_sel_hi:[1,0]
	v_pk_add_f32 v[90:91], v[88:89], v[96:97] op_sel_hi:[1,0]
	v_lshlrev_b32_e32 v88, 16, v100
	v_and_b32_e32 v89, 0xffff0000, v100
	v_mul_f32_e32 v88, v92, v88
	v_mul_f32_e32 v89, v93, v89
	v_pk_add_f32 v[94:95], v[94:95], v[96:97] op_sel_hi:[1,0]
	v_cvt_pk_bf16_f32 v88, v88, v89
	v_lshlrev_b32_e32 v89, 16, v101
	v_and_b32_e32 v92, 0xffff0000, v101
	v_mul_f32_e32 v89, v94, v89
	v_mul_f32_e32 v92, v95, v92
	v_cvt_pk_bf16_f32 v89, v89, v92
	v_lshlrev_b32_e32 v92, 16, v102
	v_mul_f32_e32 v90, v90, v92
	v_and_b32_e32 v92, 0xffff0000, v102
	v_mul_f32_e32 v91, v91, v92
	v_cvt_pk_bf16_f32 v90, v90, v91
	v_lshlrev_b32_e32 v91, 16, v103
	v_mul_f32_e32 v91, v104, v91
	v_and_b32_e32 v92, 0xffff0000, v103
	v_mul_f32_e32 v92, v105, v92
	v_cvt_pk_bf16_f32 v91, v91, v92
	global_store_dwordx4 v[98:99], v[88:91], off
	s_waitcnt vmcnt(9)
	s_nop 2
	v_mov_b32_e32 v88, v180
	v_mov_b32_e32 v89, v181
	v_mov_b32_e32 v90, v182
	v_mov_b32_e32 v91, v183
	v_add_u32_e32 v193, 0x90000, v192
	global_load_dwordx4 v[176:179], v193, s[16:17]
	global_load_dwordx4 v[180:183], v193, s[16:17] offset:256
	v_pk_add_f32 v[84:85], v[84:85], v[96:97] op_sel_hi:[1,0]
	v_pk_add_f32 v[92:93], v[82:83], v[96:97] op_sel_hi:[1,0]
	v_pk_add_f32 v[82:83], v[80:81], v[96:97] op_sel_hi:[1,0]
	v_pk_add_f32 v[86:87], v[86:87], v[96:97] op_sel_hi:[1,0]
	v_lshlrev_b32_e32 v80, 16, v88
	v_and_b32_e32 v81, 0xffff0000, v88
	v_mul_f32_e32 v80, v84, v80
	v_mul_f32_e32 v81, v85, v81
	v_cvt_pk_bf16_f32 v80, v80, v81
	v_lshlrev_b32_e32 v81, 16, v89
	v_and_b32_e32 v84, 0xffff0000, v89
	v_mul_f32_e32 v81, v86, v81
	v_mul_f32_e32 v84, v87, v84
	v_cvt_pk_bf16_f32 v81, v81, v84
	v_lshlrev_b32_e32 v84, 16, v90
	v_mul_f32_e32 v82, v82, v84
	v_and_b32_e32 v84, 0xffff0000, v90
	v_mul_f32_e32 v83, v83, v84
	v_cvt_pk_bf16_f32 v82, v82, v83
	v_lshlrev_b32_e32 v83, 16, v91
	v_mul_f32_e32 v83, v92, v83
	v_and_b32_e32 v84, 0xffff0000, v91
	v_mul_f32_e32 v84, v93, v84
	v_cvt_pk_bf16_f32 v83, v83, v84
	global_store_dwordx4 v[98:99], v[80:83], off offset:256
	s_nop 1
	v_or_b32_e32 v82, 48, v136
	v_bitop3_b32 v80, v136, s9, 48 bitop3:0xc8
	v_ashrrev_i32_e32 v83, 31, v82
	v_or_b32_e32 v80, s8, v80
	v_lshlrev_b64 v[82:83], 12, v[82:83]
	v_ashrrev_i32_e32 v81, 31, v80
	v_lshl_add_u64 v[82:83], s[16:17], 0, v[82:83]
	v_lshl_add_u64 v[80:81], v[80:81], 2, s[18:19]
	v_lshl_add_u64 v[82:83], v[82:83], 0, v[134:135]
	s_waitcnt vmcnt(18)
	s_nop 2
	v_mov_b32_e32 v80, v187
	s_mov_b32 s9, 0x80000
	s_waitcnt vmcnt(10)
	s_nop 2
	v_mov_b32_e32 v84, v156
	v_mov_b32_e32 v85, v157
	v_mov_b32_e32 v86, v158
	v_mov_b32_e32 v87, v159
	v_pk_add_f32 v[76:77], v[76:77], v[80:81] op_sel_hi:[1,0]
	v_pk_add_f32 v[88:89], v[74:75], v[80:81] op_sel_hi:[1,0]
	v_pk_add_f32 v[74:75], v[72:73], v[80:81] op_sel_hi:[1,0]
	v_lshlrev_b32_e32 v72, 16, v84
	v_and_b32_e32 v73, 0xffff0000, v84
	v_mul_f32_e32 v72, v76, v72
	v_mul_f32_e32 v73, v77, v73
	v_pk_add_f32 v[78:79], v[78:79], v[80:81] op_sel_hi:[1,0]
	v_cvt_pk_bf16_f32 v72, v72, v73
	v_lshlrev_b32_e32 v73, 16, v85
	v_and_b32_e32 v76, 0xffff0000, v85
	v_mul_f32_e32 v73, v78, v73
	v_mul_f32_e32 v76, v79, v76
	v_cvt_pk_bf16_f32 v73, v73, v76
	v_lshlrev_b32_e32 v76, 16, v86
	v_mul_f32_e32 v74, v74, v76
	v_and_b32_e32 v76, 0xffff0000, v86
	v_mul_f32_e32 v75, v75, v76
	v_cvt_pk_bf16_f32 v74, v74, v75
	v_lshlrev_b32_e32 v75, 16, v87
	v_mul_f32_e32 v75, v88, v75
	v_and_b32_e32 v76, 0xffff0000, v87
	v_mul_f32_e32 v76, v89, v76
	v_cvt_pk_bf16_f32 v75, v75, v76
	global_store_dwordx4 v[82:83], v[72:75], off
	s_waitcnt vmcnt(10)
; __device__ __forceinline__ unsigned cvt_pk_bf16(float lo, float hi) { unsigned r; asm volatile("v_cvt_pk_bf16_f32 %0, %1, %2" : "=v"(r) : "v"(lo), "v"(hi)); return r; }
; __device__ __forceinline__ float bf_lo(unsigned w) { return __uint_as_float(w << 16); }
; __device__ __forceinline__ float bf_hi(unsigned w) { return __uint_as_float(w & 0xffff0000u); }
;     __device__ __forceinline__ void operator()(const f32x4 (&acc)[2][2][4][2], const Unit& u, int wr, int wc, int fr, int fq) const {
;     ...
;         for (int ai = 0; ai < 2; ++ai)
; #pragma unroll
;             for (int m = 0; m < 4; ++m) { const int row = row0 + ai * HALF + m * 16; const float bias = bs[u.pn * 128 + (row & 127)];
;                 bf16_t* rowp = U + (size_t)row * ldc + col0;
; #pragma unroll
;                 for (int bj = 0; bj < 2; ++bj) { const u32x4 uu = *(const u32x4*)(rowp + bj * HALF);
;                     const f32x4 a0 = acc[ai][bj][m][0] + bias, a1 = acc[ai][bj][m][1] + bias;
;                     u32x4 w; w.x = cvt_pk_bf16(bf_lo(uu.x) * a0[0], bf_hi(uu.x) * a0[1]); w.y = cvt_pk_bf16(bf_lo(uu.y) * a0[2], bf_hi(uu.y) * a0[3]);
;                     w.z = cvt_pk_bf16(bf_lo(uu.z) * a1[0], bf_hi(uu.z) * a1[1]); w.w = cvt_pk_bf16(bf_lo(uu.w) * a1[2], bf_hi(uu.w) * a1[3]);
;                     *(u32x4*)(rowp + bj * HALF) = w; } }
	s_nop 2
	v_mov_b32_e32 v72, v160
	v_mov_b32_e32 v73, v161
	v_mov_b32_e32 v74, v162
	v_mov_b32_e32 v75, v163
	v_add_u32_e32 v193, 0xa0000, v192
	global_load_dwordx4 v[156:159], v193, s[16:17]
	global_load_dwordx4 v[160:163], v193, s[16:17] offset:256
	v_pk_add_f32 v[68:69], v[68:69], v[80:81] op_sel_hi:[1,0]
	v_pk_add_f32 v[76:77], v[66:67], v[80:81] op_sel_hi:[1,0]
	v_pk_add_f32 v[66:67], v[64:65], v[80:81] op_sel_hi:[1,0]
	v_pk_add_f32 v[70:71], v[70:71], v[80:81] op_sel_hi:[1,0]
	v_lshlrev_b32_e32 v64, 16, v72
	v_and_b32_e32 v65, 0xffff0000, v72
	v_mul_f32_e32 v64, v68, v64
	v_mul_f32_e32 v65, v69, v65
	v_cvt_pk_bf16_f32 v64, v64, v65
	v_lshlrev_b32_e32 v65, 16, v73
	v_and_b32_e32 v68, 0xffff0000, v73
	v_mul_f32_e32 v65, v70, v65
	v_mul_f32_e32 v68, v71, v68
	v_cvt_pk_bf16_f32 v65, v65, v68
	v_lshlrev_b32_e32 v68, 16, v74
	v_mul_f32_e32 v66, v66, v68
	v_and_b32_e32 v68, 0xffff0000, v74
	v_mul_f32_e32 v67, v67, v68
	v_cvt_pk_bf16_f32 v66, v66, v67
	v_lshlrev_b32_e32 v67, 16, v75
	v_and_b32_e32 v68, 0xffff0000, v75
	v_mul_f32_e32 v67, v76, v67
	v_mul_f32_e32 v68, v77, v68
	v_cvt_pk_bf16_f32 v67, v67, v68
	v_add_co_u32_e32 v68, vcc, s9, v138
	global_store_dwordx4 v[82:83], v[64:67], off offset:256
	s_nop 0
	v_addc_co_u32_e32 v69, vcc, 0, v139, vcc
	s_waitcnt vmcnt(25)
	s_nop 2
	v_mov_b32_e32 v66, v184
	s_waitcnt vmcnt(10)
	s_nop 2
	v_mov_b32_e32 v70, v164
	v_mov_b32_e32 v71, v165
	v_mov_b32_e32 v72, v166
	v_mov_b32_e32 v73, v167
	v_lshl_add_u64 v[64:65], v[138:139], 0, s[36:37]
	s_and_b64 vcc, exec, s[6:7]
	v_pk_add_f32 v[60:61], v[60:61], v[66:67] op_sel_hi:[1,0]
	v_pk_add_f32 v[74:75], v[58:59], v[66:67] op_sel_hi:[1,0]
	v_pk_add_f32 v[58:59], v[56:57], v[66:67] op_sel_hi:[1,0]
	v_lshlrev_b32_e32 v56, 16, v70
	v_and_b32_e32 v57, 0xffff0000, v70
	v_mul_f32_e32 v56, v60, v56
	v_mul_f32_e32 v57, v61, v57
	v_pk_add_f32 v[62:63], v[62:63], v[66:67] op_sel_hi:[1,0]
	v_cvt_pk_bf16_f32 v56, v56, v57
	v_lshlrev_b32_e32 v57, 16, v71
	v_and_b32_e32 v60, 0xffff0000, v71
	v_mul_f32_e32 v57, v62, v57
	v_mul_f32_e32 v60, v63, v60
	v_cvt_pk_bf16_f32 v57, v57, v60
	v_lshlrev_b32_e32 v60, 16, v72
	v_mul_f32_e32 v58, v58, v60
	v_and_b32_e32 v60, 0xffff0000, v72
	v_mul_f32_e32 v59, v59, v60
	v_cvt_pk_bf16_f32 v58, v58, v59
	v_lshlrev_b32_e32 v59, 16, v73
	v_mul_f32_e32 v59, v74, v59
	v_and_b32_e32 v60, 0xffff0000, v73
	v_mul_f32_e32 v60, v75, v60
	v_cvt_pk_bf16_f32 v59, v59, v60
	global_store_dwordx4 v[68:69], v[56:59], off
	s_waitcnt vmcnt(10)
	s_nop 2
	v_mov_b32_e32 v56, v168
	v_mov_b32_e32 v57, v169
	v_mov_b32_e32 v58, v170
	v_mov_b32_e32 v59, v171
	v_add_u32_e32 v193, 0xb0000, v192
	global_load_dwordx4 v[164:167], v193, s[16:17]
	global_load_dwordx4 v[168:171], v193, s[16:17] offset:256
	v_pk_add_f32 v[52:53], v[52:53], v[66:67] op_sel_hi:[1,0]
	v_pk_add_f32 v[60:61], v[50:51], v[66:67] op_sel_hi:[1,0]
	v_pk_add_f32 v[50:51], v[48:49], v[66:67] op_sel_hi:[1,0]
	v_pk_add_f32 v[54:55], v[54:55], v[66:67] op_sel_hi:[1,0]
	v_lshlrev_b32_e32 v48, 16, v56
	v_and_b32_e32 v49, 0xffff0000, v56
	v_mul_f32_e32 v48, v52, v48
	v_mul_f32_e32 v49, v53, v49
	v_cvt_pk_bf16_f32 v48, v48, v49
	v_lshlrev_b32_e32 v49, 16, v57
	v_and_b32_e32 v52, 0xffff0000, v57
	v_mul_f32_e32 v49, v54, v49
	v_mul_f32_e32 v52, v55, v52
	v_cvt_pk_bf16_f32 v49, v49, v52
	v_lshlrev_b32_e32 v52, 16, v58
	v_mul_f32_e32 v50, v50, v52
	v_and_b32_e32 v52, 0xffff0000, v58
	v_mul_f32_e32 v51, v51, v52
	v_cvt_pk_bf16_f32 v50, v50, v51
	v_lshlrev_b32_e32 v51, 16, v59
	v_mul_f32_e32 v51, v60, v51
	v_and_b32_e32 v52, 0xffff0000, v59
	v_mul_f32_e32 v52, v61, v52
	v_cvt_pk_bf16_f32 v51, v51, v52
	global_store_dwordx4 v[64:65], v[48:51], off offset:256
	s_nop 1
	v_add_u32_e32 v50, 0x90, v136
	v_and_b32_e32 v48, 0x5f, v50
	v_ashrrev_i32_e32 v51, 31, v50
	v_or_b32_e32 v48, s8, v48
	v_lshlrev_b64 v[50:51], 12, v[50:51]
	v_ashrrev_i32_e32 v49, 31, v48
	v_lshl_add_u64 v[50:51], s[16:17], 0, v[50:51]
	v_lshl_add_u64 v[48:49], v[48:49], 2, s[18:19]
	v_lshl_add_u64 v[50:51], v[50:51], 0, v[134:135]
	s_waitcnt vmcnt(28)
	s_nop 2
	v_mov_b32_e32 v48, v185
	v_pk_add_f32 v[44:45], v[44:45], v[48:49] op_sel_hi:[1,0]
	s_waitcnt vmcnt(10)
	s_nop 2
	v_mov_b32_e32 v52, v176
	v_mov_b32_e32 v53, v177
	v_mov_b32_e32 v54, v178
	v_mov_b32_e32 v55, v179
	v_pk_add_f32 v[56:57], v[42:43], v[48:49] op_sel_hi:[1,0]
	v_pk_add_f32 v[42:43], v[40:41], v[48:49] op_sel_hi:[1,0]
	v_pk_add_f32 v[46:47], v[46:47], v[48:49] op_sel_hi:[1,0]
	v_pk_add_f32 v[36:37], v[36:37], v[48:49] op_sel_hi:[1,0]
	v_pk_add_f32 v[38:39], v[38:39], v[48:49] op_sel_hi:[1,0]
	v_lshlrev_b32_e32 v40, 16, v52
	v_and_b32_e32 v41, 0xffff0000, v52
	v_mul_f32_e32 v40, v44, v40
	v_mul_f32_e32 v41, v45, v41
	v_cvt_pk_bf16_f32 v40, v40, v41
	v_lshlrev_b32_e32 v41, 16, v53
	v_and_b32_e32 v44, 0xffff0000, v53
	v_mul_f32_e32 v41, v46, v41
	v_mul_f32_e32 v44, v47, v44
	v_cvt_pk_bf16_f32 v41, v41, v44
	v_lshlrev_b32_e32 v44, 16, v54
	v_mul_f32_e32 v42, v42, v44
	v_and_b32_e32 v44, 0xffff0000, v54
	v_mul_f32_e32 v43, v43, v44
	v_cvt_pk_bf16_f32 v42, v42, v43
	v_lshlrev_b32_e32 v43, 16, v55
	v_mul_f32_e32 v43, v56, v43
	v_and_b32_e32 v44, 0xffff0000, v55
	v_mul_f32_e32 v44, v57, v44
	v_cvt_pk_bf16_f32 v43, v43, v44
	global_store_dwordx4 v[50:51], v[40:43], off
	s_waitcnt vmcnt(10)
; __device__ __forceinline__ unsigned cvt_pk_bf16(float lo, float hi) { unsigned r; asm volatile("v_cvt_pk_bf16_f32 %0, %1, %2" : "=v"(r) : "v"(lo), "v"(hi)); return r; }
; __device__ __forceinline__ float bf_lo(unsigned w) { return __uint_as_float(w << 16); }
; __device__ __forceinline__ float bf_hi(unsigned w) { return __uint_as_float(w & 0xffff0000u); }
; #define PG8_BAR __builtin_amdgcn_s_barrier()
;     __device__ __forceinline__ void operator()(const f32x4 (&acc)[2][2][4][2], const Unit& u, int wr, int wc, int fr, int fq) const {
;     ...
;         for (int ai = 0; ai < 2; ++ai)
; #pragma unroll
;             for (int m = 0; m < 4; ++m) { const int row = row0 + ai * HALF + m * 16; const float bias = bs[u.pn * 128 + (row & 127)];
;                 bf16_t* rowp = U + (size_t)row * ldc + col0;
; #pragma unroll
;                 for (int bj = 0; bj < 2; ++bj) { const u32x4 uu = *(const u32x4*)(rowp + bj * HALF);
;                     const f32x4 a0 = acc[ai][bj][m][0] + bias, a1 = acc[ai][bj][m][1] + bias;
;                     u32x4 w; w.x = cvt_pk_bf16(bf_lo(uu.x) * a0[0], bf_hi(uu.x) * a0[1]); w.y = cvt_pk_bf16(bf_lo(uu.y) * a0[2], bf_hi(uu.y) * a0[3]);
;                     w.z = cvt_pk_bf16(bf_lo(uu.z) * a1[0], bf_hi(uu.z) * a1[1]); w.w = cvt_pk_bf16(bf_lo(uu.w) * a1[2], bf_hi(uu.w) * a1[3]);
;                     *(u32x4*)(rowp + bj * HALF) = w; } }
; template <class Epi, class Sched, bool ALIGN_EPI = false, bool SP2 = false>
; __device__ __forceinline__ void gemm_phase(PG8_LAS unsigned char* lds, const Gemm g, const Sched& S, const Epi& E) {
;     ...
;         if (!has_next) break;
; #pragma unroll
;         for (int a = 0; a < 2; ++a)
; #pragma unroll
;             for (int b = 0; b < 2; ++b)
; #pragma unroll
;                 for (int m = 0; m < 4; ++m)
; #pragma unroll
;                     for (int n = 0; n < 2; ++n) acc[a][b][m][n] = (f32x4){0.f, 0.f, 0.f, 0.f};
;         cur = nxt; cA = nA; cB = nB; ++ui;
;         if constexpr (ALIGN_EPI) { if (wr == 1) PG8_BAR; }
	s_nop 2
	v_mov_b32_e32 v40, v180
	v_mov_b32_e32 v41, v181
	v_mov_b32_e32 v42, v182
	v_mov_b32_e32 v43, v183
	v_pk_add_f32 v[44:45], v[34:35], v[48:49] op_sel_hi:[1,0]
	v_pk_add_f32 v[34:35], v[32:33], v[48:49] op_sel_hi:[1,0]
	v_lshlrev_b32_e32 v32, 16, v40
	v_and_b32_e32 v33, 0xffff0000, v40
	v_mul_f32_e32 v32, v36, v32
	v_mul_f32_e32 v33, v37, v33
	v_cvt_pk_bf16_f32 v32, v32, v33
	v_lshlrev_b32_e32 v33, 16, v41
	v_and_b32_e32 v36, 0xffff0000, v41
	v_mul_f32_e32 v33, v38, v33
	v_mul_f32_e32 v36, v39, v36
	v_cvt_pk_bf16_f32 v33, v33, v36
	v_lshlrev_b32_e32 v36, 16, v42
	v_mul_f32_e32 v34, v34, v36
	v_and_b32_e32 v36, 0xffff0000, v42
	v_mul_f32_e32 v35, v35, v36
	v_cvt_pk_bf16_f32 v34, v34, v35
	v_lshlrev_b32_e32 v35, 16, v43
	v_mul_f32_e32 v35, v44, v35
	v_and_b32_e32 v36, 0xffff0000, v43
	v_mul_f32_e32 v36, v45, v36
	v_cvt_pk_bf16_f32 v35, v35, v36
	global_store_dwordx4 v[50:51], v[32:35], off offset:256
	s_nop 1
	v_add_u32_e32 v34, 0xa0, v136
	v_and_b32_e32 v32, 0x6f, v34
	v_ashrrev_i32_e32 v35, 31, v34
	v_or_b32_e32 v32, s8, v32
	v_lshlrev_b64 v[34:35], 12, v[34:35]
	v_ashrrev_i32_e32 v33, 31, v32
	v_lshl_add_u64 v[34:35], s[16:17], 0, v[34:35]
	v_lshl_add_u64 v[32:33], v[32:33], 2, s[18:19]
	v_lshl_add_u64 v[34:35], v[34:35], 0, v[134:135]
	s_waitcnt vmcnt(29)
	s_nop 2
	v_mov_b32_e32 v32, v186
	v_pk_add_f32 v[28:29], v[28:29], v[32:33] op_sel_hi:[1,0]
	s_waitcnt vmcnt(8)
	s_nop 2
	v_mov_b32_e32 v36, v156
	v_mov_b32_e32 v37, v157
	v_mov_b32_e32 v38, v158
	v_mov_b32_e32 v39, v159
	v_pk_add_f32 v[40:41], v[26:27], v[32:33] op_sel_hi:[1,0]
	v_pk_add_f32 v[26:27], v[24:25], v[32:33] op_sel_hi:[1,0]
	v_pk_add_f32 v[30:31], v[30:31], v[32:33] op_sel_hi:[1,0]
	v_pk_add_f32 v[20:21], v[20:21], v[32:33] op_sel_hi:[1,0]
	v_pk_add_f32 v[22:23], v[22:23], v[32:33] op_sel_hi:[1,0]
	v_lshlrev_b32_e32 v24, 16, v36
	v_and_b32_e32 v25, 0xffff0000, v36
	v_mul_f32_e32 v24, v28, v24
	v_mul_f32_e32 v25, v29, v25
	v_cvt_pk_bf16_f32 v24, v24, v25
	v_lshlrev_b32_e32 v25, 16, v37
	v_and_b32_e32 v28, 0xffff0000, v37
	v_mul_f32_e32 v25, v30, v25
	v_mul_f32_e32 v28, v31, v28
	v_cvt_pk_bf16_f32 v25, v25, v28
	v_lshlrev_b32_e32 v28, 16, v38
	v_mul_f32_e32 v26, v26, v28
	v_and_b32_e32 v28, 0xffff0000, v38
	v_mul_f32_e32 v27, v27, v28
	v_cvt_pk_bf16_f32 v26, v26, v27
	v_lshlrev_b32_e32 v27, 16, v39
	v_mul_f32_e32 v27, v40, v27
	v_and_b32_e32 v28, 0xffff0000, v39
	v_mul_f32_e32 v28, v41, v28
	v_cvt_pk_bf16_f32 v27, v27, v28
	global_store_dwordx4 v[34:35], v[24:27], off
	s_waitcnt vmcnt(8)
	s_nop 2
	v_mov_b32_e32 v24, v160
	v_mov_b32_e32 v25, v161
	v_mov_b32_e32 v26, v162
	v_mov_b32_e32 v27, v163
	v_pk_add_f32 v[28:29], v[18:19], v[32:33] op_sel_hi:[1,0]
	v_pk_add_f32 v[18:19], v[16:17], v[32:33] op_sel_hi:[1,0]
	v_lshlrev_b32_e32 v16, 16, v24
	v_and_b32_e32 v17, 0xffff0000, v24
	v_mul_f32_e32 v16, v20, v16
	v_mul_f32_e32 v17, v21, v17
	v_cvt_pk_bf16_f32 v16, v16, v17
	v_lshlrev_b32_e32 v17, 16, v25
	v_and_b32_e32 v20, 0xffff0000, v25
	v_mul_f32_e32 v17, v22, v17
	v_mul_f32_e32 v20, v23, v20
	v_cvt_pk_bf16_f32 v17, v17, v20
	v_lshlrev_b32_e32 v20, 16, v26
	v_mul_f32_e32 v18, v18, v20
	v_and_b32_e32 v20, 0xffff0000, v26
	v_mul_f32_e32 v19, v19, v20
	v_cvt_pk_bf16_f32 v18, v18, v19
	v_lshlrev_b32_e32 v19, 16, v27
	v_mul_f32_e32 v19, v28, v19
	v_and_b32_e32 v20, 0xffff0000, v27
	v_mul_f32_e32 v20, v29, v20
	v_cvt_pk_bf16_f32 v19, v19, v20
	global_store_dwordx4 v[34:35], v[16:19], off offset:256
	s_nop 1
	v_add_u32_e32 v18, 0xb0, v136
	v_and_b32_e32 v16, 0x7f, v18
	v_ashrrev_i32_e32 v19, 31, v18
	v_or_b32_e32 v16, s8, v16
	v_lshlrev_b64 v[18:19], 12, v[18:19]
	v_ashrrev_i32_e32 v17, 31, v16
	v_lshl_add_u64 v[18:19], s[16:17], 0, v[18:19]
	v_lshl_add_u64 v[16:17], v[16:17], 2, s[18:19]
	v_lshl_add_u64 v[18:19], v[18:19], 0, v[134:135]
	s_waitcnt vmcnt(30)
	s_nop 2
	v_mov_b32_e32 v16, v187
	s_mov_b64 s[8:9], -1
	s_waitcnt vmcnt(6)
	s_nop 2
	v_mov_b32_e32 v20, v164
	v_mov_b32_e32 v21, v165
	v_mov_b32_e32 v22, v166
	v_mov_b32_e32 v23, v167
	v_pk_add_f32 v[12:13], v[12:13], v[16:17] op_sel_hi:[1,0]
	v_pk_add_f32 v[24:25], v[10:11], v[16:17] op_sel_hi:[1,0]
	v_pk_add_f32 v[10:11], v[8:9], v[16:17] op_sel_hi:[1,0]
	v_lshlrev_b32_e32 v8, 16, v20
	v_and_b32_e32 v9, 0xffff0000, v20
	v_mul_f32_e32 v8, v12, v8
	v_mul_f32_e32 v9, v13, v9
	v_pk_add_f32 v[14:15], v[14:15], v[16:17] op_sel_hi:[1,0]
	v_cvt_pk_bf16_f32 v8, v8, v9
	v_lshlrev_b32_e32 v9, 16, v21
	v_and_b32_e32 v12, 0xffff0000, v21
	v_mul_f32_e32 v9, v14, v9
	v_mul_f32_e32 v12, v15, v12
	v_cvt_pk_bf16_f32 v9, v9, v12
	v_lshlrev_b32_e32 v12, 16, v22
	v_mul_f32_e32 v10, v10, v12
	v_and_b32_e32 v12, 0xffff0000, v22
	v_mul_f32_e32 v11, v11, v12
	v_cvt_pk_bf16_f32 v10, v10, v11
	v_lshlrev_b32_e32 v11, 16, v23
	v_mul_f32_e32 v11, v24, v11
	v_and_b32_e32 v12, 0xffff0000, v23
	v_mul_f32_e32 v12, v25, v12
	v_cvt_pk_bf16_f32 v11, v11, v12
	global_store_dwordx4 v[18:19], v[8:11], off
	s_waitcnt vmcnt(6)
	s_nop 2
	v_mov_b32_e32 v8, v168
	v_mov_b32_e32 v9, v169
	v_mov_b32_e32 v10, v170
	v_mov_b32_e32 v11, v171
	v_pk_add_f32 v[4:5], v[4:5], v[16:17] op_sel_hi:[1,0]
	v_pk_add_f32 v[12:13], v[2:3], v[16:17] op_sel_hi:[1,0]
	v_pk_add_f32 v[2:3], v[0:1], v[16:17] op_sel_hi:[1,0]
	v_pk_add_f32 v[6:7], v[6:7], v[16:17] op_sel_hi:[1,0]
	v_lshlrev_b32_e32 v0, 16, v8
	v_and_b32_e32 v1, 0xffff0000, v8
	v_mul_f32_e32 v0, v4, v0
	v_mul_f32_e32 v1, v5, v1
	v_cvt_pk_bf16_f32 v0, v0, v1
	v_lshlrev_b32_e32 v1, 16, v9
	v_and_b32_e32 v4, 0xffff0000, v9
	v_mul_f32_e32 v1, v6, v1
	v_mul_f32_e32 v4, v7, v4
	v_cvt_pk_bf16_f32 v1, v1, v4
	v_lshlrev_b32_e32 v4, 16, v10
	v_mul_f32_e32 v2, v2, v4
	v_and_b32_e32 v4, 0xffff0000, v10
	v_mul_f32_e32 v3, v3, v4
	v_cvt_pk_bf16_f32 v2, v2, v3
	v_lshlrev_b32_e32 v3, 16, v11
	v_mul_f32_e32 v3, v12, v3
	v_and_b32_e32 v4, 0xffff0000, v11
	v_mul_f32_e32 v4, v13, v4
	v_cvt_pk_bf16_f32 v3, v3, v4
	global_store_dwordx4 v[18:19], v[0:3], off offset:256
	s_cbranch_vccnz .LBB0_430
	s_andn2_b64 vcc, exec, s[4:5]
	s_cbranch_vccnz .LBB0_429
	s_barrier
	s_branch .LBB0_429
